# lru_conv: hand-written loop - taps loaded together, weights in registers, next rows prefetched
# speedup vs baseline: 1.0044x; 1.0044x over previous
.LBB0_1035:
	s_or_b64 exec, exec, s[2:3]
	s_mov_b64 s[4:5], s[66:67]
	v_mov_b32_e32 v1, v178
	v_mov_b32_e32 v2, v178
	s_mov_b32 s2, s68
	v_ashrrev_i32_e32 v2, 7, v2
	s_waitcnt vmcnt(4)
	v_lshl_add_u32 v10, s2, 2, v2
	s_mov_b32 s2, 0x8000
	v_cmp_gt_i32_e32 vcc, s2, v10
	s_and_saveexec_b64 s[2:3], vcc
	s_cbranch_execz .LBB0_1044
	s_load_dwordx4 s[8:11], s[4:5], 0x50
	s_nop 0
	s_load_dwordx2 s[4:5], s[4:5], 0x120
	v_lshlrev_b32_e32 v1, 3, v1
	v_and_b32_e32 v2, 0x3f8, v1
	v_lshlrev_b32_e32 v4, 1, v2
	v_mov_b32_e32 v5, v0
	s_waitcnt lgkmcnt(0)
	v_lshl_add_u64 v[4:5], s[4:5], 0, v[4:5]
	s_mov_b64 s[6:7], 0x15200000
	v_lshl_add_u64 v[12:13], v[4:5], 0, s[6:7]
	v_lshlrev_b32_e32 v4, 2, v2
	v_mov_b32_e32 v5, v0
	v_lshl_add_u64 v[14:15], s[8:9], 0, v[4:5]
	s_mov_b64 s[6:7], 0x3000
	s_waitcnt vmcnt(3)
	v_lshl_add_u64 v[18:19], v[14:15], 0, s[6:7]
	s_mov_b64 s[6:7], 0x1000
	v_lshl_add_u64 v[20:21], v[14:15], 0, s[6:7]
	s_mov_b64 s[6:7], 0x2000
	v_lshl_add_u64 v[16:17], s[10:11], 0, v[4:5]
	s_waitcnt vmcnt(2)
	v_lshl_add_u64 v[22:23], v[14:15], 0, s[6:7]
	s_mov_b64 s[6:7], 0
	v_lshlrev_b32_e32 v24, 1, v2
	v_mov_b32_e32 v25, v0
	global_load_dwordx4 v[54:57], v[14:15], off
	global_load_dwordx4 v[58:61], v[14:15], off offset:16
	global_load_dwordx4 v[62:65], v[20:21], off
	global_load_dwordx4 v[66:69], v[20:21], off offset:16
	global_load_dwordx4 v[70:73], v[22:23], off
	global_load_dwordx4 v[74:77], v[22:23], off offset:16
	global_load_dwordx4 v[78:81], v[18:19], off
	global_load_dwordx4 v[82:85], v[18:19], off offset:16
	global_load_dwordx4 v[86:89], v[16:17], off
	global_load_dwordx4 v[90:93], v[16:17], off offset:16
	v_and_b32_e32 v1, 0x1fff, v10
	v_mov_b64_e32 v[46:47], s[4:5]
	v_mad_i64_i32 v[46:47], s[8:9], v10, s84, v[46:47]
	s_nop 0
	v_lshl_add_u64 v[46:47], v[46:47], 0, v[24:25]
	s_mov_b64 s[8:9], 0x3201000
	v_lshl_add_u64 v[46:47], v[46:47], 0, s[8:9]
	global_load_dwordx4 v[160:163], v[46:47], off
	v_mov_b32_e32 v148, 0
	v_mov_b32_e32 v149, 0
	v_mov_b32_e32 v150, 0
	v_mov_b32_e32 v151, 0
	v_mov_b32_e32 v152, 0
	v_mov_b32_e32 v153, 0
	v_mov_b32_e32 v154, 0
	v_mov_b32_e32 v155, 0
	v_mov_b32_e32 v156, 0
	v_mov_b32_e32 v157, 0
	v_mov_b32_e32 v158, 0
	v_mov_b32_e32 v159, 0
	v_cmp_ne_u32_e32 vcc, 0, v1
	s_and_saveexec_b64 s[8:9], vcc
	s_cbranch_execz .Llc_p_t2
	v_add_co_u32_e32 v48, vcc, 0xffffe000, v46
	s_nop 1
	v_addc_co_u32_e32 v49, vcc, -1, v47, vcc
	global_load_dwordx4 v[156:159], v[48:49], off offset:-1024
.Llc_p_t2:
	s_or_b64 exec, exec, s[8:9]
	v_cmp_lt_u32_e32 vcc, 1, v1
	s_and_saveexec_b64 s[8:9], vcc
	s_cbranch_execz .Llc_p_t1
	v_add_co_u32_e32 v48, vcc, 0xffffc000, v46
	s_nop 1
	v_addc_co_u32_e32 v49, vcc, -1, v47, vcc
	global_load_dwordx4 v[152:155], v[48:49], off offset:-2048
.Llc_p_t1:
	s_or_b64 exec, exec, s[8:9]
	v_cmp_lt_u32_e32 vcc, 2, v1
	s_and_saveexec_b64 s[8:9], vcc
	s_cbranch_execz .Llc_p_t0
	v_add_co_u32_e32 v48, vcc, 0xffffa000, v46
	s_nop 1
	v_addc_co_u32_e32 v49, vcc, -1, v47, vcc
	global_load_dwordx4 v[148:151], v[48:49], off offset:-3072

.Llc_loop:
	v_mov_b32_e32 v26, v148
	v_mov_b32_e32 v27, v149
	v_mov_b32_e32 v28, v150
	v_mov_b32_e32 v29, v151
	v_mov_b32_e32 v30, v152
	v_mov_b32_e32 v31, v153
	v_mov_b32_e32 v32, v154
	v_mov_b32_e32 v33, v155
	v_mov_b32_e32 v34, v156
	v_mov_b32_e32 v35, v157
	v_mov_b32_e32 v36, v158
	v_mov_b32_e32 v37, v159
	v_mov_b32_e32 v38, v160
	v_mov_b32_e32 v39, v161
	v_mov_b32_e32 v40, v162
	v_mov_b32_e32 v41, v163
	s_mov_b32 s8, s70
	v_lshl_add_u32 v42, s8, 2, v10
	s_mov_b32 s8, 0x8000
	v_cmp_gt_i32_e32 vcc, s8, v42
	s_and_saveexec_b64 s[10:11], vcc
	s_cbranch_execz .Llc_nonext
	v_and_b32_e32 v1, 0x1fff, v42
	v_mov_b64_e32 v[46:47], s[4:5]
	v_mad_i64_i32 v[46:47], s[8:9], v42, s84, v[46:47]
	s_nop 0
	v_lshl_add_u64 v[46:47], v[46:47], 0, v[24:25]
	s_mov_b64 s[8:9], 0x3201000
	v_lshl_add_u64 v[46:47], v[46:47], 0, s[8:9]
	global_load_dwordx4 v[160:163], v[46:47], off
	v_mov_b32_e32 v148, 0
	v_mov_b32_e32 v149, 0
	v_mov_b32_e32 v150, 0
	v_mov_b32_e32 v151, 0
	v_mov_b32_e32 v152, 0
	v_mov_b32_e32 v153, 0
	v_mov_b32_e32 v154, 0
	v_mov_b32_e32 v155, 0
	v_mov_b32_e32 v156, 0
	v_mov_b32_e32 v157, 0
	v_mov_b32_e32 v158, 0
	v_mov_b32_e32 v159, 0
	v_cmp_ne_u32_e32 vcc, 0, v1
	s_and_saveexec_b64 s[8:9], vcc
	s_cbranch_execz .Llc_n_t2
	v_add_co_u32_e32 v48, vcc, 0xffffe000, v46
	s_nop 1
	v_addc_co_u32_e32 v49, vcc, -1, v47, vcc
	global_load_dwordx4 v[156:159], v[48:49], off offset:-1024

.Llc_nonext:
	s_or_b64 exec, exec, s[10:11]
	v_lshlrev_b32_e32 v50, 16, v26
	v_and_b32_e32 v51, 0xffff0000, v26
	v_pk_fma_f32 v[6:7], v[54:55], v[50:51], v[86:87]
	v_lshlrev_b32_e32 v52, 16, v27
	v_and_b32_e32 v53, 0xffff0000, v27
	v_pk_fma_f32 v[8:9], v[56:57], v[52:53], v[88:89]
	v_lshlrev_b32_e32 v50, 16, v28
	v_and_b32_e32 v51, 0xffff0000, v28
	v_pk_fma_f32 v[2:3], v[58:59], v[50:51], v[90:91]
	v_lshlrev_b32_e32 v52, 16, v29
	v_and_b32_e32 v53, 0xffff0000, v29
	v_pk_fma_f32 v[4:5], v[60:61], v[52:53], v[92:93]
	v_lshlrev_b32_e32 v50, 16, v30
	v_and_b32_e32 v51, 0xffff0000, v30
	v_pk_fma_f32 v[6:7], v[62:63], v[50:51], v[6:7]
	v_lshlrev_b32_e32 v52, 16, v31
	v_and_b32_e32 v53, 0xffff0000, v31
	v_pk_fma_f32 v[8:9], v[64:65], v[52:53], v[8:9]
	v_lshlrev_b32_e32 v50, 16, v32
	v_and_b32_e32 v51, 0xffff0000, v32
	v_pk_fma_f32 v[2:3], v[66:67], v[50:51], v[2:3]
	v_lshlrev_b32_e32 v52, 16, v33
	v_and_b32_e32 v53, 0xffff0000, v33
	v_pk_fma_f32 v[4:5], v[68:69], v[52:53], v[4:5]
	v_lshlrev_b32_e32 v50, 16, v34
	v_and_b32_e32 v51, 0xffff0000, v34
	v_pk_fma_f32 v[6:7], v[70:71], v[50:51], v[6:7]
	v_lshlrev_b32_e32 v52, 16, v35
	v_and_b32_e32 v53, 0xffff0000, v35
	v_pk_fma_f32 v[8:9], v[72:73], v[52:53], v[8:9]
	v_lshlrev_b32_e32 v50, 16, v36
	v_and_b32_e32 v51, 0xffff0000, v36
	v_pk_fma_f32 v[2:3], v[74:75], v[50:51], v[2:3]
	v_lshlrev_b32_e32 v52, 16, v37
	v_and_b32_e32 v53, 0xffff0000, v37
	v_pk_fma_f32 v[4:5], v[76:77], v[52:53], v[4:5]
	v_lshlrev_b32_e32 v50, 16, v38
	v_and_b32_e32 v51, 0xffff0000, v38
	v_pk_fma_f32 v[6:7], v[78:79], v[50:51], v[6:7]
	v_lshlrev_b32_e32 v52, 16, v39
	v_and_b32_e32 v53, 0xffff0000, v39
	v_pk_fma_f32 v[8:9], v[80:81], v[52:53], v[8:9]
	v_lshlrev_b32_e32 v50, 16, v40
	v_and_b32_e32 v51, 0xffff0000, v40
	v_pk_fma_f32 v[2:3], v[82:83], v[50:51], v[2:3]
	v_lshlrev_b32_e32 v52, 16, v41
	v_and_b32_e32 v53, 0xffff0000, v41
	v_pk_fma_f32 v[4:5], v[84:85], v[52:53], v[4:5]
	v_cvt_pk_bf16_f32 v50, v6, v7
	v_cvt_pk_bf16_f32 v51, v8, v9
	v_cvt_pk_bf16_f32 v52, v2, v3
	v_cvt_pk_bf16_f32 v53, v4, v5
	v_lshlrev_b32_e32 v44, 11, v10
	v_mov_b32_e32 v45, v0
	v_lshl_add_u64 v[44:45], v[12:13], 0, v[44:45]
	global_store_dwordx4 v[44:45], v[50:53], off
	s_waitcnt vmcnt(1)
	v_mov_b32_e32 v10, v42
	s_movk_i32 s8, 0x7fff
	v_cmp_lt_i32_e32 vcc, s8, v10
	s_or_b64 s[6:7], vcc, s[6:7]
	s_andn2_b64 exec, exec, s[6:7]
	s_cbranch_execnz .Llc_loop
